# P5 epilogue pipelined; P8 and P5: workgroups with bit 3 of their id set run their K-slice unit first (per-XCD epilogue traffic of the two halves interleaves)
# speedup vs baseline: 1.0080x; 1.0007x over previous
;     __host__ __device__ __forceinline__ bool next(int i, Unit& u) const {
;         const long L = (long)i * G + c; if (L >= nwg + 32 * NSPLIT) return false;
;         Unit a; map(L < nwg ? (int)L : 0, a);
;         const bool sp = L >= nwg; const int j = sp ? (int)L - nwg : 0, tile = j / NSPLIT, ks = j % NSPLIT, base = nch / NSPLIT, rem = nch % NSPLIT;
;         u.pm = sp ? 64 + (tile >> 3) : a.pm; u.pn = sp ? (tile & 7) : a.pn; u.ks = sp ? ks : -1;
;         u.k0 = sp ? (ks * base + (ks < rem ? ks : rem)) * 128 : 0; u.nt = sp ? (base + (ks < rem ? 1 : 0)) * 2 : ntk; return true;
.LBB0_947:
	s_or_b64 exec, exec, s[4:5]
	s_mov_b64 s[4:5], s[0:1]
	s_waitcnt lgkmcnt(0)
	v_mov_b32_e32 v0, v254
	v_mov_b32_e32 v8, v254
	s_cmpk_lt_i32 s2, 0x300
	s_barrier
	s_cselect_b64 s[18:19], -1, 0
	s_cmpk_gt_i32 s2, 0x2ff
	v_readfirstlane_b32 s20, v8
	s_cbranch_scc1 .LBB0_984
	s_bitcmp1_b32 s2, 3
	s_cselect_b32 s99, 0x200, 0
	s_cmpk_eq_u32 s48, 0x100
	s_cselect_b32 s99, s99, 0
	s_add_i32 s2, s2, s99
	s_cmpk_gt_i32 s2, 0x1ff
	s_cselect_b64 s[8:9], -1, 0
	s_ashr_i32 s3, s2, 31
	s_lshr_b32 s6, s3, 29
	s_add_i32 s14, s2, s6
	s_and_b32 s6, s14, -8
	s_sub_i32 s6, s2, s6
	s_cmpk_lt_i32 s2, 0x200
	s_cselect_b32 s10, s6, 0
	s_cmp_gt_i32 s10, -1
	s_cbranch_scc0 .LBB0_950
	s_lshl_b32 s15, s10, 6
	s_cbranch_execz .LBB0_951
	s_branch .LBB0_952

; #define PG8_STAGE(bufoff, gbase, voff) do { _Pragma("unroll") for (int _i = 0; _i < 2; ++_i) \
;         __builtin_amdgcn_global_load_lds((const unsigned*)((const char*)(gbase) + (voff)[_i]), (PG8_LAS unsigned*)(lds + (bufoff) + ldsw + _i * 8192), 16, 0, 0); } while (0)
; #define PG8_WAIT_V(n) asm volatile("s_waitcnt vmcnt(" #n ")" ::: "memory")
; #define PG8_BAR __builtin_amdgcn_s_barrier()
; template <class Epi, class Sched, bool ALIGN_EPI = false, bool SP2 = false>
; __device__ __forceinline__ void gemm_phase(PG8_LAS unsigned char* lds, const Gemm g, const Sched& S, const Epi& E) {
;     ...
;     for (int i = 0; i < 2; ++i) { int R, C; stage_rc(tid * 16 + i * 8192, R, C); const int Rb = Epi::PERM ? ((R & ~31) + perm32(R & 31)) : R;
;         voffA[i] = (unsigned)(R * g.lda + C) * 2u; voffB[i] = (unsigned)(Rb * g.ldb + C) * 2u; }
;     const size_t kstep = (size_t)(BK * 2);
;     const size_t hstepA = (size_t)HALF * g.lda * 2, hstepB = (size_t)HALF * g.ldb * 2;
;     const unsigned ldsw = (unsigned)wid * 1024u;
;     const int aoff = lds_byte(wr * 64 + fr, fq * 8), boff = lds_byte(wc * 32 + fr, fq * 8);
;     ...
;         PG8_STAGE(PG8_SB(0, 0), cB, voffB); PG8_STAGE(PG8_SB(0, 1), cB + hstepB, voffB); PG8_STAGE(PG8_SA(0, 0), cA, voffA); PG8_STAGE(PG8_SA(0, 1), cA + hstepA, voffA);
;         if (wr == 1) PG8_BAR;
;         PG8_WAIT_V(2); PG8_BAR;
.LBB0_956:
	s_sub_i32 s2, s2, s99
	v_ashrrev_i32_e32 v1, 31, v8
	v_lshrrev_b32_e32 v1, 26, v1
	v_add_u32_e32 v1, v8, v1
	v_ashrrev_i32_e32 v9, 6, v1
	v_bfe_i32 v1, v8, 27, 1
	v_lshlrev_b32_e32 v0, 4, v8
	v_lshrrev_b32_e32 v1, 22, v1
	v_add_u32_e32 v1, v0, v1
	v_and_b32_e32 v1, 0xfffffc00, v1
	v_sub_u32_e32 v1, v0, v1
	v_lshrrev_b32_e32 v2, 4, v1
	v_bitop3_b32 v1, v2, v1, 32 bitop3:0x6c
	v_ashrrev_i32_e32 v3, 31, v1
	v_lshrrev_b32_e32 v3, 26, v3
	v_add_u32_e32 v3, v1, v3
	v_lshlrev_b32_e32 v2, 3, v9
	v_ashrrev_i32_e32 v10, 6, v3
	v_and_b32_e32 v3, 0xc0, v3
	v_and_b32_e32 v2, -16, v2
	v_sub_u32_e32 v1, v1, v3
	v_mov_b32_e32 v3, 1
	v_add_u32_e32 v2, v10, v2
	v_ashrrev_i16_sdwa v1, v3, sext(v1) dst_sel:DWORD dst_unused:UNUSED_PAD src0_sel:DWORD src1_sel:BYTE_0
	v_lshlrev_b32_e32 v4, 5, v9
	v_bfe_i32 v11, v1, 0, 16
	v_lshlrev_b32_e32 v1, 1, v2
	v_lshrrev_b32_e32 v5, 2, v2
	v_and_b32_e32 v6, 3, v10
	s_mov_b32 s9, 0xfffe0
	v_and_b32_e32 v4, 32, v4
	v_and_b32_e32 v1, 24, v1
	v_and_b32_e32 v5, 4, v5
	v_and_or_b32 v6, v2, s9, v6
	v_or3_b32 v1, v6, v5, v1
	v_add_lshl_u32 v4, v4, v11, 1
	v_add_u32_e32 v0, 0x2000, v0
	v_lshl_add_u32 v146, v1, 12, v4
	v_ashrrev_i32_e32 v1, 31, v0
	v_lshrrev_b32_e32 v1, 22, v1
	v_add_u32_e32 v1, v0, v1
	v_ashrrev_i32_e32 v12, 10, v1
	v_mul_i32_i24_e32 v1, 0x400, v12
	v_sub_u32_e32 v0, v0, v1
	v_lshrrev_b32_e32 v1, 4, v0
	v_bitop3_b32 v0, v1, v0, 32 bitop3:0x6c
	v_lshl_add_u32 v144, v2, 12, v4
	v_ashrrev_i32_e32 v2, 31, v0
	s_waitcnt lgkmcnt(0)
	s_add_u32 s23, s6, 0x2500000
	v_lshrrev_b32_e32 v2, 26, v2
	s_addc_u32 s45, s7, 0
	v_add_u32_e32 v2, v0, v2
	s_add_u32 s47, s6, 0x18000000
	v_lshlrev_b32_e32 v1, 3, v12
	v_ashrrev_i32_e32 v13, 6, v2
	v_and_b32_e32 v2, 0xc0, v2
	s_addc_u32 s62, s7, 0
	v_and_b32_e32 v1, -16, v1
	v_sub_u32_e32 v0, v0, v2
	s_ashr_i32 s16, s20, 6
	s_ashr_i32 s53, s52, 31
	s_ashr_i32 s21, s20, 8
	v_add_u32_e32 v1, v13, v1
	v_ashrrev_i16_sdwa v0, v3, sext(v0) dst_sel:DWORD dst_unused:UNUSED_PAD src0_sel:DWORD src1_sel:BYTE_0
	v_and_b32_e32 v3, 3, v13
	s_lshl_b32 s63, s16, 10
	s_lshl_b64 s[12:13], s[52:53], 20
	v_and_or_b32 v3, v1, s9, v3
	s_add_u32 s9, s47, s12
	s_addc_u32 s14, s62, s13
	s_ashr_i32 s55, s54, 31
	s_lshl_b64 s[12:13], s[54:55], 20
	s_add_u32 s12, s23, s12
	s_addc_u32 s13, s45, s13
	s_lshl_b64 s[10:11], s[10:11], 1
	s_add_u32 s58, s12, s10
	v_lshlrev_b32_e32 v4, 5, v12
	v_bfe_i32 v14, v0, 0, 16
	v_lshlrev_b32_e32 v0, 1, v1
	v_lshrrev_b32_e32 v2, 2, v1
	s_addc_u32 s59, s13, s11
	s_add_i32 s53, s63, 0
	v_and_b32_e32 v4, 32, v4
	v_and_b32_e32 v0, 24, v0
	v_and_b32_e32 v2, 4, v2
	s_add_i32 m0, s53, 0x10000
	v_or3_b32 v0, v3, v2, v0
	v_add_lshl_u32 v2, v4, v14, 1
	global_load_lds_dwordx4 v146, s[58:59]
	s_add_i32 m0, s53, 0x12000
	v_lshl_add_u32 v150, v0, 12, v2
	s_add_u32 s12, s58, 0x80000
	global_load_lds_dwordx4 v150, s[58:59]
	s_addc_u32 s13, s59, 0
	s_add_i32 m0, s53, 0x14000
	v_lshl_add_u32 v148, v1, 12, v2
	global_load_lds_dwordx4 v146, s[12:13]
	s_add_i32 m0, s53, 0x16000
	s_add_u32 s56, s9, s10
	s_addc_u32 s57, s14, s11
	s_add_i32 s64, s53, 0x2000
	global_load_lds_dwordx4 v150, s[12:13]
	s_mov_b32 m0, s53
	s_add_u32 s10, s56, 0x80000
	global_load_lds_dwordx4 v144, s[56:57]
	s_mov_b32 m0, s64
	s_addc_u32 s11, s57, 0
	s_add_i32 s65, s53, 0x4000
	global_load_lds_dwordx4 v148, s[56:57]
	s_mov_b32 m0, s65
	s_add_i32 s66, s53, 0x6000
	global_load_lds_dwordx4 v144, s[10:11]
	s_mov_b32 m0, s66
	v_mov_b32_e32 v147, 0
	global_load_lds_dwordx4 v148, s[10:11]
	s_load_dwordx2 s[10:11], s[4:5], 0x0
	v_mov_b32_e32 v151, v147
	v_mov_b32_e32 v145, v147
	v_mov_b32_e32 v149, v147
	s_cmp_eq_u32 s21, 1
	s_mov_b32 s9, 0
	v_lshl_add_u64 v[6:7], s[58:59], 0, v[146:147]
	v_lshl_add_u64 v[4:5], s[58:59], 0, v[150:151]
	v_lshl_add_u64 v[0:1], s[56:57], 0, v[144:145]
	s_cselect_b64 s[12:13], -1, 0
	s_cmp_lg_u32 s21, 1
	v_lshl_add_u64 v[2:3], s[56:57], 0, v[148:149]
	s_cbranch_scc1 .LBB0_958
	s_barrier

;     __host__ __device__ __forceinline__ bool next(int i, Unit& u) const {
;         const long L = (long)i * G + c; if (L >= nwg + 32 * NSPLIT) return false;
;         Unit a; map(L < nwg ? (int)L : 0, a);
;         const bool sp = L >= nwg; const int j = sp ? (int)L - nwg : 0, tile = j / NSPLIT, ks = j % NSPLIT, base = nch / NSPLIT, rem = nch % NSPLIT;
;         u.pm = sp ? 64 + (tile >> 3) : a.pm; u.pn = sp ? (tile & 7) : a.pn; u.ks = sp ? ks : -1;
;         u.k0 = sp ? (ks * base + (ks < rem ? ks : rem)) * 128 : 0; u.nt = sp ? (base + (ks < rem ? 1 : 0)) * 2 : ntk; return true;
; template <class Epi, class Sched, bool ALIGN_EPI = false, bool SP2 = false>
; __device__ __forceinline__ void gemm_phase(PG8_LAS unsigned char* lds, const Gemm g, const Sched& S, const Epi& E) {
;     ...
;         const bool has_next = S.next(ui + 1, nxt);
.LBB0_961:
	s_add_i32 s77, s77, 1
	s_mul_i32 s4, s77, s73
	s_mul_hi_u32 s5, s77, s74
	s_add_i32 s5, s5, s4
	s_mul_i32 s4, s77, s74
	s_add_u32 s42, s4, s2
	s_addc_u32 s43, s5, s3
	s_bitcmp1_b32 s2, 3
	s_cselect_b32 s98, 0x100, 0
	s_cmpk_eq_u32 s48, 0x100
	s_cselect_b32 s98, s98, 0
	s_cmpk_lt_u32 s42, 0x300
	s_cselect_b32 s98, s98, 0
	s_sub_u32 s42, s42, s98
	v_cmp_gt_i64_e32 vcc, s[42:43], v[158:159]
	v_cmp_lt_i64_e64 s[4:5], s[42:43], v[156:157]
	s_cbranch_vccnz .LBB0_970
	s_ashr_i32 s36, s42, 31
	s_lshr_b32 s36, s36, 29
	s_add_i32 s39, s42, s36
	s_and_b32 s36, s39, -8
	v_cmp_lt_i64_e32 vcc, s[42:43], v[162:163]
	s_sub_i32 s38, s42, s36
	s_and_b64 s[36:37], vcc, exec
	s_cselect_b32 s38, s38, 0
	v_cmp_gt_i64_e64 s[6:7], s[42:43], v[160:161]
	s_cmp_gt_i32 s38, -1
	s_mov_b64 s[36:37], -1
	s_cbranch_scc0 .LBB0_964
	s_lshl_b32 s43, s38, 6
	s_cbranch_execnz .LBB0_966
	s_branch .LBB0_965
